# A1 indexer unit prologue: q-block and head-weight loads issued together with one wait (was 3 serialized round trips); key loop relu: max(0,x) without separate canonicalize
# speedup vs baseline: 1.0073x; 1.0073x over previous
; #define LAS __attribute__((address_space(3)))
; template <int PARTS> DI void idx_unit(const bf16_t* PROJ, unsigned long long* MASK64, float* scr, LAS unsigned char* lds, int b, int qb, int tid, int wave, int lane) {
;     ...
;     LAS float* wl = (LAS float*)lds;
;     if (tid < 128) { const int q = tid >> 2, hh = tid & 3; wl[tid] = __uint_as_float((unsigned)PROJ[(rowbase + q0 + q) * NINP + C_WI + hh] << 16); }
;     const int r = lane & 31, h = lane >> 5;
;     constexpr int QP = 528;
;     LAS unsigned char* ql = lds + 512;
; #pragma unroll
;     for (int p = 0; p < 2; ++p) { const int idx = tid + 512 * p, row = idx >> 5, ch = idx & 31;
;         *(LAS u32x4*)(ql + row * QP + ch * 16) = *(const u32x4*)(PROJ + (rowbase + q0 + row) * NINP + C_QI + ch * 8); }
;     __syncthreads();
;     const int nkb = (PARTS & 1) ? q0 / 32 + 1 : 0;
;     bf16x8 kfn[4];
; #pragma unroll
;     for (int ks = 0; ks < 4; ++ks) kfn[ks] = *(const bf16x8*)(PROJ + (rowbase + (wave < nkb ? wave : 0) * 32 + r) * NINP + C_KI + ks * 16 + h * 8);
; #pragma unroll 1
;     for (int kb = wave; kb < nkb; kb += 8) {
;         bf16x8 kf[4];
; #pragma unroll
;         for (int ks = 0; ks < 4; ++ks) kf[ks] = kfn[ks];
;         { const int kbn = kb + 8 < nkb ? kb + 8 : kb;
; #pragma unroll
;           for (int ks = 0; ks < 4; ++ks) kfn[ks] = *(const bf16x8*)(PROJ + (rowbase + kbn * 32 + r) * NINP + C_KI + ks * 16 + h * 8); }
.LBB0_434:
	s_ashr_i32 s6, s0, 5
	s_and_b32 s0, s0, 31
	s_and_b32 s1, s60, 1
	s_xor_b32 s2, s0, 63
	s_cmp_eq_u32 s1, 0
	s_cselect_b32 s4, s2, s0
	s_ashr_i32 s7, s6, 31
	s_lshl_b32 s91, s4, 5
	v_writelane_b32 v255, s6, 13
	v_mov_b32_e32 v0, v98
	s_cmp_gt_u32 s4, 7
	v_writelane_b32 v255, s7, 14
	s_mov_b64 s[0:1], -1
	s_cbranch_scc0 .LBB0_488
	v_readlane_b32 s0, v255, 13
	v_readlane_b32 s1, v255, 14
	s_lshl_b64 s[96:97], s[0:1], 11
	s_or_b32 s0, s96, s91
	s_mov_b32 s1, s97
	v_lshl_add_u64 v[2:3], s[0:1], 0, v[204:205]
	v_mad_u64_u32 v[4:5], s[2:3], v2, s90, v[214:215]
	v_mov_b32_e32 v2, v5
	v_mad_u64_u32 v[2:3], s[2:3], v3, s90, v[2:3]
	v_mov_b32_e32 v5, v2
	global_load_dwordx4 v[6:9], v[4:5], off offset:1280
	s_mov_b64 s[2:3], exec
	v_readlane_b32 s6, v254, 2
	v_readlane_b32 s7, v254, 3
	s_and_b64 s[6:7], s[2:3], s[6:7]
	s_mov_b64 exec, s[6:7]
	s_cbranch_execz .LBB0_437
	v_readlane_b32 s6, v254, 60
	v_readlane_b32 s7, v254, 61
	v_lshl_add_u64 v[2:3], s[0:1], 0, v[200:201]
	v_mov_b32_e32 v221, v98
	v_mov_b64_e32 v[4:5], s[6:7]
	v_mad_u64_u32 v[4:5], s[6:7], v2, s90, v[4:5]
	v_mov_b32_e32 v2, v5
	v_mad_u64_u32 v[2:3], s[6:7], v3, s90, v[2:3]
	v_mov_b32_e32 v5, v2
	v_lshl_add_u64 v[2:3], v[4:5], 0, v[220:221]
	v_add_co_u32_e32 v2, vcc, 0x2000, v2
	s_nop 1
	v_addc_co_u32_e32 v3, vcc, 0, v3, vcc
	global_load_ushort v1, v[2:3], off offset:896
.LBB0_437:
	s_or_b64 exec, exec, s[2:3]
	v_lshl_add_u64 v[2:3], s[0:1], 0, v[206:207]
	v_mad_u64_u32 v[4:5], s[0:1], v2, s90, v[214:215]
	v_mov_b32_e32 v2, v5
	v_mad_u64_u32 v[2:3], s[0:1], v3, s90, v[2:3]
	v_mov_b32_e32 v5, v2
	global_load_dwordx4 v[10:13], v[4:5], off offset:1280
	s_waitcnt vmcnt(0)
	ds_write_b128 v240, v[6:9] offset:512
	ds_write_b128 v241, v[10:13] offset:512
	s_mov_b64 s[2:3], exec
	v_readlane_b32 s6, v254, 2
	v_readlane_b32 s7, v254, 3
	s_and_b64 exec, s[2:3], s[6:7]
	v_lshlrev_b32_e32 v1, 16, v1
	ds_write_b32 v203, v1
	s_mov_b64 exec, s[2:3]
	v_readlane_b32 s0, v254, 1
	s_cmp_gt_i32 s0, s4
	s_waitcnt lgkmcnt(0)
	s_barrier
	s_cbranch_scc1 .LBB0_441
	v_lshl_add_u64 v[2:3], s[96:97], 0, v[208:209]
	v_mad_u64_u32 v[4:5], s[0:1], v2, s90, v[216:217]
	v_mov_b32_e32 v2, v5
	v_mad_u64_u32 v[2:3], s[0:1], v3, s90, v[2:3]
	v_mov_b32_e32 v5, v2
	global_load_dwordx4 v[192:195], v[4:5], off offset:1792
	global_load_dwordx4 v[188:191], v[4:5], off offset:1824
	global_load_dwordx4 v[184:187], v[4:5], off offset:1856
	global_load_dwordx4 v[180:183], v[4:5], off offset:1888
	ds_read_b128 v[32:35], v242 offset:512
	ds_read_b128 v[36:39], v242 offset:544
	ds_read_b128 v[40:43], v242 offset:576
	ds_read_b128 v[44:47], v242 offset:608
	ds_read_b128 v[48:51], v213
	ds_read_b128 v[52:55], v213 offset:16
	ds_read_b128 v[56:59], v213 offset:32
	ds_read_b128 v[60:63], v213 offset:48
	ds_read_b128 v[64:67], v213 offset:128
	ds_read_b128 v[68:71], v213 offset:144
	ds_read_b128 v[72:75], v213 offset:160
	ds_read_b128 v[76:79], v213 offset:176
	ds_read_b128 v[80:83], v213 offset:256
	ds_read_b128 v[84:87], v213 offset:272
	ds_read_b128 v[88:91], v213 offset:288
	ds_read_b128 v[92:95], v213 offset:304
	ds_read_b128 v[100:103], v213 offset:384
	ds_read_b128 v[104:107], v213 offset:400
	ds_read_b128 v[108:111], v213 offset:416
	ds_read_b128 v[112:115], v213 offset:432
	ds_read_b128 v[116:119], v242 offset:640
	ds_read_b128 v[120:123], v242 offset:672
	ds_read_b128 v[124:127], v242 offset:704
	ds_read_b128 v[128:131], v242 offset:736
	ds_read_b128 v[132:135], v242 offset:768
	ds_read_b128 v[136:139], v242 offset:800
	ds_read_b128 v[140:143], v242 offset:832
	ds_read_b128 v[144:147], v242 offset:864
	ds_read_b128 v[148:151], v242 offset:896
	ds_read_b128 v[152:155], v242 offset:928
	ds_read_b128 v[156:159], v242 offset:960
	ds_read_b128 v[160:163], v242 offset:992
	v_mov_b64_e32 v[196:197], 0x200
	v_mov_b32_e32 v223, s97
	v_or_b32_e32 v222, s96, v202
	v_mov_b32_e32 v1, v0
	v_mov_b32_e32 v2, v0
	v_mov_b32_e32 v3, v0
	v_mov_b32_e32 v4, v0
	v_mov_b32_e32 v5, v0
	v_mov_b32_e32 v6, v0
	v_mov_b32_e32 v7, v0
	v_mov_b32_e32 v8, v0
	v_mov_b32_e32 v9, v0
	v_mov_b32_e32 v10, v0
	v_mov_b32_e32 v11, v0
	v_mov_b32_e32 v12, v0
	v_mov_b32_e32 v13, v0
	v_mov_b32_e32 v14, v0
	v_mov_b32_e32 v15, v0
	v_mov_b32_e32 v224, v238
	v_readlane_b32 s1, v254, 1
; #define LAS __attribute__((address_space(3)))
; #define MFMA32(a, b, c) __builtin_amdgcn_mfma_f32_32x32x16_bf16((a), (b), (c), 0, 0, 0)
; DI int crow(int i, int h) { return (i & 3) + 8 * (i >> 2) + 4 * h; }
; template <int PARTS> DI void idx_unit(const bf16_t* PROJ, unsigned long long* MASK64, float* scr, LAS unsigned char* lds, int b, int qb, int tid, int wave, int lane) {
;     ...
; #pragma unroll 1
;     for (int kb = wave; kb < nkb; kb += 8) {
;         bf16x8 kf[4];
; #pragma unroll
;         for (int ks = 0; ks < 4; ++ks) kf[ks] = kfn[ks];
;         { const int kbn = kb + 8 < nkb ? kb + 8 : kb;
; #pragma unroll
;           for (int ks = 0; ks < 4; ++ks) kfn[ks] = *(const bf16x8*)(PROJ + (rowbase + kbn * 32 + r) * NINP + C_KI + ks * 16 + h * 8); }
;         f32x16 sc;
; #pragma unroll
;         for (int i = 0; i < 16; ++i) sc[i] = zf_;
; #pragma unroll
;         for (int hh = 0; hh < 4; ++hh) {
;             f32x16 x;
; #pragma unroll
;             for (int i = 0; i < 16; ++i) x[i] = zf_;
; #pragma unroll
;             for (int ks = 0; ks < 4; ++ks) { const bf16x8 qfr = *(const LAS bf16x8*)(ql + r * QP + hh * 128 + ks * 32 + h * 16); x = MFMA32(qfr, kf[ks], x); }
; #pragma unroll
;             for (int i = 0; i < 16; ++i) { const float wv = wl[crow(i, h) * 4 + hh]; sc[i] = __builtin_fmaf(wv, __builtin_fmaxf(x[i], 0.f), sc[i]); }
;         }
.LBB0_439:
	s_add_i32 s0, s1, 8
	s_cmp_gt_i32 s0, s4
	s_cselect_b32 s1, s1, s0
	s_lshl_b32 s2, s1, 5
	s_ashr_i32 s3, s2, 31
	v_lshl_add_u64 v[16:17], v[222:223], 0, s[2:3]
	v_mad_u64_u32 v[18:19], s[2:3], v16, s90, v[216:217]
	v_mad_i32_i24 v19, v17, s90, v19
	global_load_dwordx4 v[172:175], v[18:19], off offset:1792
	global_load_dwordx4 v[168:171], v[18:19], off offset:1824
	global_load_dwordx4 v[164:167], v[18:19], off offset:1856
	global_load_dwordx4 v[176:179], v[18:19], off offset:1888
	s_waitcnt vmcnt(7) lgkmcnt(14)
	v_mfma_f32_32x32x16_bf16 v[16:31], v[32:35], v[192:195], v[0:15]
	s_cmp_le_i32 s0, s4
	s_mov_b32 s1, s0
	s_waitcnt vmcnt(6)
	v_mfma_f32_32x32x16_bf16 v[16:31], v[36:39], v[188:191], v[16:31]
	s_waitcnt vmcnt(5)
	v_mfma_f32_32x32x16_bf16 v[16:31], v[40:43], v[184:187], v[16:31]
	s_waitcnt vmcnt(4)
	v_mfma_f32_32x32x16_bf16 v[16:31], v[44:47], v[180:183], v[16:31]
	s_nop 11
	v_max_f32_e32 v16, 0, v16
	v_fma_f32 v227, v48, v16, v0
	v_max_f32_e32 v16, 0, v17
	v_fma_f32 v226, v52, v16, v0
	v_max_f32_e32 v16, 0, v18
	v_fma_f32 v228, v56, v16, v0
	v_max_f32_e32 v16, 0, v19
	v_fma_f32 v232, v60, v16, v0
	v_max_f32_e32 v16, 0, v20
	v_fma_f32 v252, v64, v16, v0
	v_max_f32_e32 v16, 0, v21
	v_fma_f32 v251, v68, v16, v0
	v_max_f32_e32 v16, 0, v22
	v_fma_f32 v250, v72, v16, v0
	v_max_f32_e32 v16, 0, v23
	v_fma_f32 v249, v76, v16, v0
	v_max_f32_e32 v16, 0, v24
	v_fma_f32 v248, v80, v16, v0
	v_max_f32_e32 v16, 0, v25
	v_fma_f32 v247, v84, v16, v0
	v_max_f32_e32 v16, 0, v26
	v_fma_f32 v246, v88, v16, v0
	v_max_f32_e32 v16, 0, v27
	v_fma_f32 v245, v92, v16, v0
	v_max_f32_e32 v16, 0, v28
	v_fma_f32 v244, v100, v16, v0
	v_max_f32_e32 v16, 0, v29
	v_fma_f32 v243, v104, v16, v0
	v_max_f32_e32 v16, 0, v30
	s_waitcnt lgkmcnt(13)
	v_fma_f32 v225, v108, v16, v0
	v_max_f32_e32 v16, 0, v31
	s_waitcnt lgkmcnt(12)
	v_fma_f32 v221, v112, v16, v0
	s_waitcnt lgkmcnt(11)
	v_mfma_f32_32x32x16_bf16 v[16:31], v[116:119], v[192:195], v[0:15]
	s_waitcnt lgkmcnt(10)
	v_mfma_f32_32x32x16_bf16 v[16:31], v[120:123], v[188:191], v[16:31]
	s_waitcnt lgkmcnt(9)
	v_mfma_f32_32x32x16_bf16 v[16:31], v[124:127], v[184:187], v[16:31]
	s_waitcnt lgkmcnt(8)
	v_mfma_f32_32x32x16_bf16 v[16:31], v[128:131], v[180:183], v[16:31]
	s_nop 11
	v_max_f32_e32 v16, 0, v16
	v_fmac_f32_e32 v227, v49, v16
	v_max_f32_e32 v16, 0, v17
	v_fmac_f32_e32 v226, v53, v16
	v_max_f32_e32 v16, 0, v18
	v_fmac_f32_e32 v228, v57, v16
	v_max_f32_e32 v16, 0, v19
	v_fmac_f32_e32 v232, v61, v16
	v_max_f32_e32 v16, 0, v20
	v_fmac_f32_e32 v252, v65, v16
	v_max_f32_e32 v16, 0, v21
	v_fmac_f32_e32 v251, v69, v16
	v_max_f32_e32 v16, 0, v22
	v_fmac_f32_e32 v250, v73, v16
	v_max_f32_e32 v16, 0, v23
	v_fmac_f32_e32 v249, v77, v16
	v_max_f32_e32 v16, 0, v24
	v_fmac_f32_e32 v248, v81, v16
	v_max_f32_e32 v16, 0, v25
	v_fmac_f32_e32 v247, v85, v16
	v_max_f32_e32 v16, 0, v26
	v_fmac_f32_e32 v246, v89, v16
	v_max_f32_e32 v16, 0, v27
	v_fmac_f32_e32 v245, v93, v16
	v_max_f32_e32 v16, 0, v28
	v_fmac_f32_e32 v244, v101, v16
	v_max_f32_e32 v16, 0, v29
	v_fmac_f32_e32 v243, v105, v16
	v_max_f32_e32 v16, 0, v30
	v_fmac_f32_e32 v225, v109, v16
	v_max_f32_e32 v16, 0, v31
	v_fmac_f32_e32 v221, v113, v16
	s_waitcnt lgkmcnt(7)
	v_mfma_f32_32x32x16_bf16 v[16:31], v[132:135], v[192:195], v[0:15]
	s_waitcnt lgkmcnt(6)
	v_mfma_f32_32x32x16_bf16 v[16:31], v[136:139], v[188:191], v[16:31]
	s_waitcnt lgkmcnt(5)
	v_mfma_f32_32x32x16_bf16 v[16:31], v[140:143], v[184:187], v[16:31]
	s_waitcnt lgkmcnt(4)
	v_mfma_f32_32x32x16_bf16 v[16:31], v[144:147], v[180:183], v[16:31]
	s_nop 11
	v_max_f32_e32 v16, 0, v16
	v_fmac_f32_e32 v227, v50, v16
	v_max_f32_e32 v16, 0, v17
	v_fmac_f32_e32 v226, v54, v16
	v_max_f32_e32 v16, 0, v18
	v_fmac_f32_e32 v228, v58, v16
	v_max_f32_e32 v16, 0, v19
	v_fmac_f32_e32 v232, v62, v16
	v_max_f32_e32 v16, 0, v20
	v_fmac_f32_e32 v252, v66, v16
	v_max_f32_e32 v16, 0, v21
	v_fmac_f32_e32 v251, v70, v16
	v_max_f32_e32 v16, 0, v22
	v_fmac_f32_e32 v250, v74, v16
	v_max_f32_e32 v16, 0, v23
	v_fmac_f32_e32 v249, v78, v16
	v_max_f32_e32 v16, 0, v24
	v_fmac_f32_e32 v248, v82, v16
	v_max_f32_e32 v16, 0, v25
	v_fmac_f32_e32 v247, v86, v16
	v_max_f32_e32 v16, 0, v26
	v_fmac_f32_e32 v246, v90, v16
	v_max_f32_e32 v16, 0, v27
	v_fmac_f32_e32 v245, v94, v16
	v_max_f32_e32 v16, 0, v28
	v_fmac_f32_e32 v244, v102, v16
	v_max_f32_e32 v16, 0, v29
	v_fmac_f32_e32 v243, v106, v16
	v_max_f32_e32 v16, 0, v30
	v_fmac_f32_e32 v225, v110, v16
	v_max_f32_e32 v16, 0, v31
	v_fmac_f32_e32 v221, v114, v16
	s_waitcnt lgkmcnt(3)
	v_mfma_f32_32x32x16_bf16 v[16:31], v[148:151], v[192:195], v[0:15]
	s_waitcnt vmcnt(3)
; #define LAS __attribute__((address_space(3)))
; #define MFMA32(a, b, c) __builtin_amdgcn_mfma_f32_32x32x16_bf16((a), (b), (c), 0, 0, 0)
; DI int crow(int i, int h) { return (i & 3) + 8 * (i >> 2) + 4 * h; }
; template <int PARTS> DI void idx_unit(const bf16_t* PROJ, unsigned long long* MASK64, float* scr, LAS unsigned char* lds, int b, int qb, int tid, int wave, int lane) {
;     ...
;         for (int ks = 0; ks < 4; ++ks) kf[ks] = kfn[ks];
;         { const int kbn = kb + 8 < nkb ? kb + 8 : kb;
; #pragma unroll
;           for (int ks = 0; ks < 4; ++ks) kfn[ks] = *(const bf16x8*)(PROJ + (rowbase + kbn * 32 + r) * NINP + C_KI + ks * 16 + h * 8); }
;         f32x16 sc;
; #pragma unroll
;         for (int i = 0; i < 16; ++i) sc[i] = zf_;
; #pragma unroll
;         for (int hh = 0; hh < 4; ++hh) {
;             f32x16 x;
; #pragma unroll
;             for (int i = 0; i < 16; ++i) x[i] = zf_;
; #pragma unroll
;             for (int ks = 0; ks < 4; ++ks) { const bf16x8 qfr = *(const LAS bf16x8*)(ql + r * QP + hh * 128 + ks * 32 + h * 16); x = MFMA32(qfr, kf[ks], x); }
; #pragma unroll
;             for (int i = 0; i < 16; ++i) { const float wv = wl[crow(i, h) * 4 + hh]; sc[i] = __builtin_fmaf(wv, __builtin_fmaxf(x[i], 0.f), sc[i]); }
;         }
; #pragma unroll
;         for (int i = 0; i < 16; ++i) scr[crow(i, h) * SEQ + kb * 32 + r] = sc[i] + 0.f;
;     }
	v_mov_b32_e32 v192, v172
	v_mov_b32_e32 v193, v173
	v_mov_b32_e32 v194, v174
	v_mov_b32_e32 v195, v175
	s_waitcnt lgkmcnt(2)
	v_mfma_f32_32x32x16_bf16 v[16:31], v[152:155], v[188:191], v[16:31]
	s_waitcnt vmcnt(2)
	v_mov_b32_e32 v188, v168
	v_mov_b32_e32 v189, v169
	v_mov_b32_e32 v190, v170
	v_mov_b32_e32 v191, v171
	s_waitcnt lgkmcnt(1)
	v_mfma_f32_32x32x16_bf16 v[16:31], v[156:159], v[184:187], v[16:31]
	s_waitcnt vmcnt(1)
	v_mov_b32_e32 v184, v164
	v_mov_b32_e32 v185, v165
	v_mov_b32_e32 v186, v166
	v_mov_b32_e32 v187, v167
	s_waitcnt lgkmcnt(0)
	v_mfma_f32_32x32x16_bf16 v[16:31], v[160:163], v[180:183], v[16:31]
	s_waitcnt vmcnt(0)
	v_mov_b64_e32 v[182:183], v[178:179]
	v_mov_b64_e32 v[180:181], v[176:177]
	s_nop 8
	v_max_f32_e32 v16, 0, v16
	v_fmac_f32_e32 v227, v51, v16
	v_max_f32_e32 v16, 0, v17
	v_fmac_f32_e32 v226, v55, v16
	v_max_f32_e32 v16, 0, v18
	v_fmac_f32_e32 v228, v59, v16
	v_max_f32_e32 v16, 0, v19
	v_fmac_f32_e32 v232, v63, v16
	v_max_f32_e32 v16, 0, v20
	v_fmac_f32_e32 v252, v67, v16
	v_max_f32_e32 v16, 0, v21
	v_fmac_f32_e32 v251, v71, v16
	v_max_f32_e32 v16, 0, v22
	v_fmac_f32_e32 v250, v75, v16
	v_max_f32_e32 v16, 0, v23
	v_fmac_f32_e32 v249, v79, v16
	v_max_f32_e32 v16, 0, v24
	v_fmac_f32_e32 v248, v83, v16
	v_max_f32_e32 v16, 0, v25
	v_fmac_f32_e32 v247, v87, v16
	v_max_f32_e32 v16, 0, v26
	v_fmac_f32_e32 v246, v91, v16
	v_max_f32_e32 v16, 0, v27
	v_fmac_f32_e32 v245, v95, v16
	v_max_f32_e32 v16, 0, v28
	v_fmac_f32_e32 v244, v103, v16
	v_max_f32_e32 v16, 0, v29
	v_fmac_f32_e32 v243, v107, v16
	v_max_f32_e32 v16, 0, v30
	v_fmac_f32_e32 v225, v111, v16
	v_max_f32_e32 v16, 0, v31
	v_fmac_f32_e32 v221, v115, v16
	v_add_u32_e32 v16, 0xffff2800, v224
	v_ashrrev_i32_e32 v17, 31, v16
	v_add_f32_e32 v18, 0, v227
	v_lshl_add_u64 v[16:17], v[16:17], 2, s[52:53]
	global_store_dword v[16:17], v18, off
	v_add_u32_e32 v16, 0xffff3000, v224
	v_ashrrev_i32_e32 v17, 31, v16
	v_add_f32_e32 v18, 0, v226
	v_lshl_add_u64 v[16:17], v[16:17], 2, s[52:53]
	global_store_dword v[16:17], v18, off
	v_add_u32_e32 v16, 0xffff3800, v224
	v_ashrrev_i32_e32 v17, 31, v16
	v_add_f32_e32 v18, 0, v228
	v_lshl_add_u64 v[16:17], v[16:17], 2, s[52:53]
	global_store_dword v[16:17], v18, off
	v_add_u32_e32 v16, 0xffff4000, v224
	v_ashrrev_i32_e32 v17, 31, v16
	v_add_f32_e32 v18, 0, v232
	v_lshl_add_u64 v[16:17], v[16:17], 2, s[52:53]
	global_store_dword v[16:17], v18, off
	v_add_u32_e32 v16, 0xffff6800, v224
	v_ashrrev_i32_e32 v17, 31, v16
	v_add_f32_e32 v18, 0, v252
	v_lshl_add_u64 v[16:17], v[16:17], 2, s[52:53]
	global_store_dword v[16:17], v18, off
	v_add_u32_e32 v16, 0xffff7000, v224
	v_ashrrev_i32_e32 v17, 31, v16
	v_add_f32_e32 v18, 0, v251
	v_lshl_add_u64 v[16:17], v[16:17], 2, s[52:53]
	global_store_dword v[16:17], v18, off
	v_add_u32_e32 v16, 0xffff7800, v224
	v_ashrrev_i32_e32 v17, 31, v16
	v_add_f32_e32 v18, 0, v250
	v_lshl_add_u64 v[16:17], v[16:17], 2, s[52:53]
	global_store_dword v[16:17], v18, off
	v_add_u32_e32 v16, 0xffff8000, v224
	v_ashrrev_i32_e32 v17, 31, v16
	v_add_f32_e32 v18, 0, v249
	v_lshl_add_u64 v[16:17], v[16:17], 2, s[52:53]
	global_store_dword v[16:17], v18, off
	v_add_u32_e32 v16, 0xffffa800, v224
	v_ashrrev_i32_e32 v17, 31, v16
	v_add_f32_e32 v18, 0, v248
	v_lshl_add_u64 v[16:17], v[16:17], 2, s[52:53]
	global_store_dword v[16:17], v18, off
	v_add_u32_e32 v16, 0xffffb000, v224
	v_ashrrev_i32_e32 v17, 31, v16
	v_add_f32_e32 v18, 0, v247
	v_lshl_add_u64 v[16:17], v[16:17], 2, s[52:53]
	global_store_dword v[16:17], v18, off
	v_add_u32_e32 v16, 0xffffb800, v224
	v_ashrrev_i32_e32 v17, 31, v16
	v_add_f32_e32 v18, 0, v246
	v_lshl_add_u64 v[16:17], v[16:17], 2, s[52:53]
	global_store_dword v[16:17], v18, off
	v_add_u32_e32 v16, 0xffffc000, v224
	v_ashrrev_i32_e32 v17, 31, v16
	v_add_f32_e32 v18, 0, v245
	v_lshl_add_u64 v[16:17], v[16:17], 2, s[52:53]
	global_store_dword v[16:17], v18, off
	v_add_u32_e32 v16, 0xffffe800, v224
	v_ashrrev_i32_e32 v17, 31, v16
	v_add_f32_e32 v18, 0, v244
	v_lshl_add_u64 v[16:17], v[16:17], 2, s[52:53]
	global_store_dword v[16:17], v18, off
	v_add_u32_e32 v16, 0xfffff000, v224
	v_ashrrev_i32_e32 v17, 31, v16
	v_add_f32_e32 v18, 0, v243
	v_lshl_add_u64 v[16:17], v[16:17], 2, s[52:53]
	global_store_dword v[16:17], v18, off
	v_add_u32_e32 v16, 0xfffff800, v224
	v_ashrrev_i32_e32 v17, 31, v16
	v_add_f32_e32 v18, 0, v225
	v_lshl_add_u64 v[16:17], v[16:17], 2, s[52:53]
	v_ashrrev_i32_e32 v225, 31, v224
	global_store_dword v[16:17], v18, off
	v_add_f32_e32 v18, 0, v221
	v_lshl_add_u64 v[16:17], v[224:225], 2, s[52:53]
	v_add_u32_e32 v224, 0x100, v224
	global_store_dword v[16:17], v18, off
	s_cbranch_scc1 .LBB0_439
	v_mov_b32_e32 v252, 0x1000
	v_mov_b64_e32 v[246:247], v[196:197]
